# attention unit: the workgroup barrier after the last g-loop iteration removed (the epilogue is register-only; the next unit's LDS writes are fenced by the unit-start barrier)
# speedup vs baseline: 1.0098x; 1.0085x over previous
; #define ATT_BAR() do { asm volatile("s_waitcnt lgkmcnt(0)" ::: "memory"); __builtin_amdgcn_s_barrier(); asm volatile("" ::: "memory"); } while (0)
; #define ATT_LD(j, KR, VR) do { KR = *(const u32x4*)(Kb + (kg0 + (long)(j) * 64 * D)); VR = *(const u32x4*)(Vt + (vg0 + (long)(j) * 64)); } while (0)
; #define ATT_ST(j, KR, VR) do { LAS unsigned char* kd_ = lds + ATT_KS + ((j) & 3) * KS_TILE + lr * KS_PITCH + pc * 16; LAS unsigned char* vd_ = lds + ATT_VS + ((j) & 3) * VS_TILE + lr * VS_PITCH + (pc >> 1) * 32 + (pc & 1) * 8;     \
;         *(LAS u32x4*)kd_ = KR; *(LAS u32x2*)vd_ = (u32x2){VR.x, VR.y}; *(LAS u32x2*)(vd_ + 16) = (u32x2){VR.z, VR.w}; } while (0)
; __device__ __forceinline__ void attn_phase(LAS unsigned char* lds, const bf16_t* Q, const bf16_t* Kb, const bf16_t* Vt, bf16_t* O, const float* relb, const float* qn, const float* kn, int vcu, int G) {
;     ...
;             ATT_BAR();
;             if (g + 2 <= 11) ATT_ST(g + 2, kreg, vreg);
;             if (g + 3 <= 11) ATT_LD(g + 3, kreg, vreg);
;             if (actg) ATT_SM(sc0, sc1, pw);
;             ATT_BAR();
;         }
;         if (half == 0) ATT_BAR();
;         const float lt = lrun + __shfl_xor(lrun, 32), il = 1.f / lt;
.Lag_exit:
	s_waitcnt lgkmcnt(0)
.LBB0_471:
	s_and_b64 vcc, exec, s[36:37]
	s_cbranch_vccz .LBB0_435
	s_waitcnt lgkmcnt(0)
	s_barrier
	s_branch .LBB0_435
